# v15: v12 + FF1 prologue's static same-row-panel check loop skipped + spurious compiler vmcnt waits after the template's wait removed in the P5/P8/P9 phase prologues
# speedup vs baseline: 1.0082x; 1.0007x over previous
.LBB0_1332:
	s_add_u32 s8, s2, 0x53000000
	s_addc_u32 s9, s3, 0
	s_add_u32 s10, s2, 0x2f000000
	s_addc_u32 s11, s3, 0
	s_add_u32 s12, s2, 0x33000000
	s_addc_u32 s13, s3, 0
	s_add_u32 s14, s2, 0x39000000
	s_addc_u32 s15, s3, 0
	s_and_b32 s43, s16, 3
	s_lshl_b32 s44, s17, 6
	s_lshl_b32 s45, s43, 5
	s_add_u32 s2, s30, 0x80
	s_waitcnt vmcnt(2)
	s_barrier
	s_addc_u32 s3, s31, 0
	s_add_i32 m0, s1, 0x18000
	s_nop 0
	global_load_lds_dwordx4 v211, s[2:3]
	v_and_b32_e32 v1, 15, v0
	s_add_i32 m0, s1, 0x1a000
	s_nop 0
	global_load_lds_dwordx4 v212, s[2:3]
	s_add_u32 s2, s28, 0x80
	s_addc_u32 s3, s29, 0
	s_add_i32 m0, s1, 0x8000
	s_nop 0
	global_load_lds_dwordx4 v211, s[2:3]
	v_lshrrev_b32_e32 v3, 3, v0
	s_add_i32 m0, s1, 0xa000
	s_nop 0
	global_load_lds_dwordx4 v212, s[2:3]
	v_lshrrev_b32_e32 v0, 1, v0
	s_add_u32 s2, s30, 0x40080
	v_and_b32_e32 v3, 6, v3
	v_and_b32_e32 v4, 5, v0
	s_addc_u32 s3, s31, 0
	s_add_i32 m0, s1, 0x1c000
	s_nop 0
	global_load_lds_dwordx4 v211, s[2:3]
	v_or_b32_e32 v2, s44, v1
	v_or_b32_e32 v1, s45, v1
	v_bitop3_b32 v0, v0, v3, 5 bitop3:0x6c
	v_bitop3_b32 v3, v3, v4, 1 bitop3:0x36
	s_add_i32 m0, s1, 0x1e000
	s_nop 0
	global_load_lds_dwordx4 v212, s[2:3]
	v_lshlrev_b32_e32 v2, 7, v2
	v_lshlrev_b32_e32 v1, 7, v1
	v_lshlrev_b32_e32 v0, 4, v0
	v_lshlrev_b32_e32 v3, 4, v3
	s_cmpk_lt_u32 s0, 0x100
	v_or_b32_e32 v5, v2, v0
	v_or_b32_e32 v2, v3, v2
	v_or_b32_e32 v0, v1, v0
	v_or_b32_e32 v1, v1, v3
	s_cselect_b64 s[16:17], -1, 0
	v_add_u32_e32 v3, 64, v204
	s_add_i32 s0, 0, 0x10000
	v_cmp_lt_i32_e32 vcc, v206, v3
	v_add_u32_e32 v216, s0, v0
	v_add_u32_e32 v217, s0, v1
	s_add_i32 s0, 0, 0x14000
	s_waitcnt vmcnt(6)
	v_cndmask_b32_e32 v4, v223, v206, vcc
	v_cmp_lt_i32_e32 vcc, v205, v3
	v_add_u32_e32 v218, s0, v0
	v_add_u32_e32 v219, s0, v1
	s_add_i32 s0, 0, 0x18000
	v_cndmask_b32_e32 v3, v223, v205, vcc
	v_add_u32_e32 v222, s0, v0
	v_add_u32_e32 v225, s0, v1
	s_add_i32 s0, 0, 0x1c000
	v_lshlrev_b32_e32 v214, 2, v4
	v_lshlrev_b32_e32 v215, 2, v3
	s_mov_b32 s19, 0
	s_ashr_i32 s46, s85, 31
	v_mov_b64_e32 v[160:161], 0x400
	v_mov_b64_e32 v[162:163], 0x3ff
	v_add_u32_e32 v220, 0, v5
	v_add_u32_e32 v221, 0, v2
	v_add_u32_e32 v226, s0, v0
	v_add_u32_e32 v227, s0, v1
	s_mov_b32 s47, 0xc2fe0000
	s_mov_b32 s48, 0x40c0c00
	v_mov_b32_e32 v228, 0x42fe0000
	s_mov_b32 s49, 0
	s_barrier
	s_branch .LBB0_1335

.LBB0_1574:
	s_ashr_i32 s48, s85, 31
	s_add_i32 s1, s85, s74
	s_add_u32 s8, s85, s74
	s_addc_u32 s9, s48, s75
	s_mov_b64 s[12:13], -1
	v_mov_b64_e32 v[0:1], 0x800
	v_mov_b64_e32 v[2:3], 0x7ff
	s_mov_b64 s[4:5], -1
	s_branch .LBB0_1584

.LBB0_1595:
	s_add_u32 s8, s10, 0x3d000000
	s_addc_u32 s9, s11, 0
	s_add_u32 s10, s10, 0x10000
	v_and_b32_e32 v1, 48, v0
	v_lshlrev_b32_e32 v2, 6, v0
	s_movk_i32 s14, 0x3c0
	v_lshlrev_b32_e32 v0, 2, v0
	s_sext_i32_i16 s57, s4
	s_addc_u32 s11, s11, 0
	s_lshl_b32 s4, s5, 13
	v_and_or_b32 v1, v2, s14, v1
	v_and_b32_e32 v0, 32, v0
	v_bitop3_b32 v2, v1, s4, v0 bitop3:0xde
	s_lshl_b32 s4, s13, 5
	s_and_b32 s46, s4, 0x60
	s_lshl_b32 s31, s5, 6
	s_lshl_b32 s4, s46, 7
	s_add_u32 s14, s36, 0x80
	s_waitcnt vmcnt(2)
	s_barrier
	s_addc_u32 s15, s37, 0
	s_add_i32 m0, s0, 0x18000
	s_nop 0
	global_load_lds_dwordx4 v152, s[14:15]
	v_bitop3_b32 v0, s4, v1, v0 bitop3:0xf6
	s_add_i32 m0, s0, 0x1a000
	s_nop 0
	global_load_lds_dwordx4 v153, s[14:15]
	s_add_u32 s14, s34, 0x80
	s_addc_u32 s15, s35, 0
	s_add_i32 m0, s0, 0x8000
	s_nop 0
	global_load_lds_dwordx4 v152, s[14:15]
	v_add_u32_e32 v0, 0, v0
	s_add_i32 m0, s0, 0xa000
	s_nop 0
	global_load_lds_dwordx4 v153, s[14:15]
	s_add_u32 s14, s36, 0x100080
	s_addc_u32 s15, s37, 0
	s_add_i32 m0, s0, 0x1c000
	s_nop 0
	global_load_lds_dwordx4 v152, s[14:15]
	s_mov_b32 s47, 0
	s_add_i32 m0, s0, 0x1e000
	s_nop 0
	global_load_lds_dwordx4 v153, s[14:15]
	s_cmpk_lt_u32 s12, 0x100
	s_waitcnt vmcnt(6)
	s_cselect_b64 s[12:13], -1, 0
	s_lshl_b32 s4, s5, 8
	s_add_i32 s50, s4, 0
	s_add_i32 s49, s50, 0x20000
	s_add_i32 s50, s50, 0x20200
	v_mov_b64_e32 v[144:145], 0x800
	v_mov_b64_e32 v[146:147], 0x7ff
	v_add_u32_e32 v154, 0x10000, v0
	v_add_u32_e32 v155, 0x14000, v0
	v_add_u32_e32 v156, 0, v2
	v_add_u32_e32 v157, 0x18000, v0
	v_add_u32_e32 v158, 0x1c000, v0
	s_mov_b64 s[14:15], 0x400000
	s_mov_b32 s51, 0x400000
	s_mov_b64 s[16:17], 0x480000
	s_mov_b32 s52, 0x480000
	s_mov_b64 s[18:19], 0x500000
	s_mov_b32 s53, 0x500000
	s_mov_b64 s[20:21], 0x580000
	s_mov_b32 s56, 0x580000
	s_barrier
	s_branch .LBB0_1598

.LBB0_1671:
	s_add_u32 s8, s6, 0x1d000000
	s_addc_u32 s9, s7, 0
	s_add_u32 s6, s6, 0x214000
	s_sext_i32_i8 s40, s0
	s_addc_u32 s7, s7, 0
	s_lshl_b32 s21, s11, 6
	v_and_b32_e32 v0, 48, v224
	s_lshl_b32 s0, s11, 13
	v_lshlrev_b32_e32 v1, 6, v224
	s_movk_i32 s11, 0x3c0
	v_and_or_b32 v0, v1, s11, v0
	v_lshlrev_b32_e32 v1, 2, v224
	v_and_b32_e32 v1, 32, v1
	v_bitop3_b32 v2, v0, s0, v1 bitop3:0xde
	s_lshl_b32 s0, s10, 5
	s_and_b32 s38, s0, 0x60
	s_lshl_b32 s0, s38, 7
	s_add_u32 s10, s24, 0x80
	s_waitcnt vmcnt(2)
	s_barrier
	s_addc_u32 s11, s25, 0
	s_add_i32 m0, s33, 0x18000
	s_nop 0
	global_load_lds_dwordx4 v156, s[10:11]
	v_bitop3_b32 v0, s0, v0, v1 bitop3:0xf6
	s_add_i32 m0, s33, 0x1a000
	s_nop 0
	global_load_lds_dwordx4 v157, s[10:11]
	s_add_u32 s10, s22, 0x80
	s_addc_u32 s11, s23, 0
	s_add_i32 m0, s33, 0x8000
	s_nop 0
	global_load_lds_dwordx4 v156, s[10:11]
	v_add_u32_e32 v0, 0, v0
	s_add_i32 m0, s33, 0xa000
	s_nop 0
	global_load_lds_dwordx4 v157, s[10:11]
	s_add_u32 s10, s24, 0x400080
	s_addc_u32 s11, s25, 0
	s_add_i32 m0, s33, 0x1c000
	s_nop 0
	global_load_lds_dwordx4 v156, s[10:11]
	s_mov_b32 s39, 0
	s_add_i32 m0, s33, 0x1e000
	s_nop 0
	global_load_lds_dwordx4 v157, s[10:11]
	s_waitcnt vmcnt(6)
	s_cmpk_lt_u32 s1, 0x100
	s_cselect_b64 s[10:11], -1, 0
	v_mov_b64_e32 v[144:145], 0x200
	v_mov_b64_e32 v[146:147], 0x1ff
	v_add_u32_e32 v158, 0x10000, v0
	v_add_u32_e32 v159, 0x14000, v0
	v_add_u32_e32 v160, 0, v2
	v_add_u32_e32 v161, 0x18000, v0
	v_add_u32_e32 v162, 0x1c000, v0
	s_barrier
	s_branch .LBB0_1674
